# combined: v tile stores through an LDS transpose (full lines), mid-block setprio pairs dropped, gate/up late start for the short workgroups, 64-bit accumulator zeroing, odd workgroups run the residual
# speedup vs baseline: 1.0066x; 1.0057x over previous
; #define PG8_WAIT_V(n) asm volatile("s_waitcnt vmcnt(" #n ")" ::: "memory")
; #define PG8_BAR __builtin_amdgcn_s_barrier()
; template <class Epi>
; __device__ __forceinline__ void gemm_phase(LAS unsigned char* lds, const Gemm g, const Epi& E) {
;     ...
;         const char* nA = has_next ? (const char*)((nxt.sub & 1) ? g.A1 : g.A0) + (size_t)nxt.pm * tstep + (size_t)nxt.kt0 * kstep : cA; const char* nB = has_next ? (const char*)((nxt.sub & 1) ? g.B1 : g.B0) + (size_t)nxt.pn * tstep + (size_t)nxt.kt0 * kstep : cB;
;         const int nt = cur.nt;
;         for (int t = 0; t < nt; t += 2) {
;             const bool last = (t == nt - 2);
;             const char* a1 = cA + (size_t)(t + 1) * kstep;
;             const char* a2 = last ? nA : cA + (size_t)(t + 2) * kstep; const char* b2 = last ? nB : cB + (size_t)(t + 2) * kstep;
;             const char* a3 = a2 + kstep; const char* b3 = b2 + kstep;
;             PG8_LDB(B0, 0, 0); PG8_LDB(B1, 0, 1); PG8_SCHED; PG8_LDA(At, 0, 0); PG8_STAGE(PG8_SA(1, 1), a1 + hstep, voffA);
;             PG8_WAIT_V(8); PG8_WAIT_L(0); PG8_BAR; PG8_MMA(0, 0, At, B0); PG8_MMA(0, 1, At, B1); PG8_BAR; PG8_SCHED;
;             PG8_LDA(At, 0, 1); PG8_STAGE(PG8_SB(0, 0), b2, voffA); PG8_STAGE(PG8_SB(0, 1), b2 + hstep, voffA); PG8_STAGE(PG8_SA(0, 0), a2, voffA);
;             PG8_WAIT_V(8); PG8_WAIT_L(0); PG8_BAR; PG8_MMA(1, 0, At, B0); PG8_MMA(1, 1, At, B1); PG8_BAR; PG8_SCHED;
;             PG8_LDB(B0, 1, 0); PG8_LDB(B1, 1, 1); PG8_SCHED; PG8_LDA(At, 1, 0); PG8_STAGE(PG8_SA(0, 1), a2 + hstep, voffA);
;             PG8_WAIT_V(8); PG8_WAIT_L(0); PG8_BAR; PG8_MMA(0, 0, At, B0); PG8_MMA(0, 1, At, B1); PG8_BAR; PG8_SCHED;
;             PG8_LDA(At, 1, 1); PG8_STAGE(PG8_SB(1, 0), b3, voffA); PG8_STAGE(PG8_SB(1, 1), b3 + hstep, voffA); PG8_STAGE(PG8_SA(1, 0), a3, voffA);
;             PG8_WAIT_V(8); PG8_WAIT_L(0); PG8_BAR; PG8_MMA(1, 0, At, B0); PG8_MMA(1, 1, At, B1); PG8_BAR; PG8_SCHED;
;         }
;         if (wr == 0) PG8_BAR;
;         E(acc, cur, wr, wc, fr, fq);
;         if (!has_next) break;
;         if (!(Epi::KEEP && cur.sub == 0))
; #pragma unroll
;         for (int a = 0; a < 2; ++a)
; #pragma unroll
;             for (int b = 0; b < 2; ++b)
; #pragma unroll
;                 for (int m = 0; m < 4; ++m)
; #pragma unroll
;                     for (int n = 0; n < 2; ++n) acc[a][b][m][n] = (f32x4){0.f, 0.f, 0.f, 0.f};
.LBB0_93:
	s_ashr_i32 s69, s68, 31
	s_lshl_b64 s[10:11], s[68:69], 19
	s_add_u32 s2, s35, s10
	s_addc_u32 s12, s28, s11
	s_ashr_i32 s75, s74, 31
	s_lshl_b64 s[10:11], s[74:75], 7
	s_add_u32 s58, s2, s10
	s_addc_u32 s59, s12, s11
	s_ashr_i32 s71, s70, 31
	s_lshl_b64 s[12:13], s[70:71], 19
	s_add_u32 s2, s29, s12
	s_addc_u32 s12, s45, s13
	s_add_u32 s62, s2, s10
	s_addc_u32 s63, s12, s11
	s_cmp_lt_i32 s72, 1
	s_cbranch_scc1 .LBB0_268
	s_and_b64 s[10:11], s[6:7], exec
	s_cselect_b32 s2, s59, s9
	s_cselect_b32 s12, s58, s8
	s_cselect_b32 s13, s63, s5
	s_cselect_b32 s15, s62, s4
	s_add_i32 s69, s72, -2
	s_add_u32 s8, s8, 0x40080
	s_addc_u32 s9, s9, 0
	s_add_u32 s71, s4, 0x100
	s_addc_u32 s75, s5, 0
	s_mov_b32 s4, 0
	v_mov_b64_e32 v[2:3], 0
	v_mov_b64_e32 v[4:5], 0
	v_mov_b64_e32 v[6:7], 0
	v_mov_b64_e32 v[8:9], 0
	v_mov_b64_e32 v[10:11], 0
	v_mov_b64_e32 v[12:13], 0
	v_mov_b64_e32 v[14:15], 0
	v_mov_b64_e32 v[16:17], 0
	v_mov_b64_e32 v[18:19], 0
	v_mov_b64_e32 v[20:21], 0
	v_mov_b64_e32 v[22:23], 0
	v_mov_b64_e32 v[24:25], 0
	v_mov_b64_e32 v[26:27], 0
	v_mov_b64_e32 v[28:29], 0
	v_mov_b64_e32 v[30:31], 0
	v_mov_b64_e32 v[32:33], 0
	v_mov_b64_e32 v[34:35], 0
	v_mov_b64_e32 v[36:37], 0
	v_mov_b64_e32 v[38:39], 0
	v_mov_b64_e32 v[40:41], 0
	v_mov_b64_e32 v[42:43], 0
	v_mov_b64_e32 v[44:45], 0
	v_mov_b64_e32 v[46:47], 0
	v_mov_b64_e32 v[48:49], 0
	v_mov_b64_e32 v[50:51], 0
	v_mov_b64_e32 v[52:53], 0
	v_mov_b64_e32 v[54:55], 0
	v_mov_b64_e32 v[56:57], 0
	v_mov_b64_e32 v[58:59], 0
	v_mov_b64_e32 v[60:61], 0
	v_mov_b64_e32 v[62:63], 0
	v_mov_b64_e32 v[64:65], 0
	v_mov_b64_e32 v[66:67], 0
	v_mov_b64_e32 v[68:69], 0
	v_mov_b64_e32 v[70:71], 0
	v_mov_b64_e32 v[72:73], 0
	v_mov_b64_e32 v[74:75], 0
	v_mov_b64_e32 v[76:77], 0
	v_mov_b64_e32 v[78:79], 0
	v_mov_b64_e32 v[80:81], 0
	v_mov_b64_e32 v[82:83], 0
	v_mov_b64_e32 v[84:85], 0
	v_mov_b64_e32 v[86:87], 0
	v_mov_b64_e32 v[88:89], 0
	v_mov_b64_e32 v[90:91], 0
	v_mov_b64_e32 v[92:93], 0
	v_mov_b64_e32 v[94:95], 0
	v_mov_b64_e32 v[96:97], 0
	v_mov_b64_e32 v[98:99], 0
	v_mov_b64_e32 v[100:101], 0
	v_mov_b64_e32 v[102:103], 0
	v_mov_b64_e32 v[104:105], 0
	v_mov_b64_e32 v[106:107], 0
	v_mov_b64_e32 v[108:109], 0
	v_mov_b64_e32 v[110:111], 0
	v_mov_b64_e32 v[112:113], 0
	v_mov_b64_e32 v[114:115], 0
	v_mov_b64_e32 v[116:117], 0
	v_mov_b64_e32 v[118:119], 0
	v_mov_b64_e32 v[120:121], 0
	v_mov_b64_e32 v[122:123], 0
	v_mov_b64_e32 v[124:125], 0
	v_mov_b64_e32 v[126:127], 0
	v_mov_b64_e32 v[128:129], 0
	s_cmp_lg_u32 s32, 0
	s_cbranch_scc1 .Lk1_peel

; __device__ __forceinline__ unsigned pk2(float lo, float hi) { const f32x2_t v = {lo, hi}; const bf16v2_t b = __builtin_convertvector(v, bf16v2_t); return __builtin_bit_cast(unsigned, b); }
;     __device__ __forceinline__ void operator()(const AccT& acc, const pg8::Unit& u, int wr, int wc, int fr_, int fq_) const {
;     ...
;         } else if (pn < 8) {
; #pragma unroll
;             for (int ai = 0; ai < 2; ++ai)
; #pragma unroll
;                 for (int m = 0; m < 4; ++m) {
;                     const int rl = rl0 + ai * 128 + m * 16;
; #pragma unroll
;                     for (int bj = 0; bj < 2; ++bj) {
;                         const int hv = 2 * (pn - 4) + bj;
; #pragma unroll
;                         for (int n = 0; n < 2; ++n) {
;                             const int dv = 32 * wc + 16 * n + 4 * fq;
;                             bf16_t* vt = VT + ((size_t)(b * NH + hv) * DV + dv) * TB + pt * 256 + rl;
;                             const f32x4 a = acc[ai][bj][m][n];
;                             const unsigned p0 = pk2(a[0], a[1]), p1 = pk2(a[2], a[3]);
;                             vt[0] = (bf16_t)(p0 & 0xffffu); vt[(size_t)TB] = (bf16_t)(p0 >> 16); vt[(size_t)2 * TB] = (bf16_t)(p1 & 0xffffu); vt[(size_t)3 * TB] = (bf16_t)(p1 >> 16);
;                         }
;                         __builtin_amdgcn_sched_barrier(0);
;                     }
;                 }
.LBB0_261:
	s_and_b64 vcc, exec, s[4:5]
	s_cbranch_vccz .LBB0_263
	v_mbcnt_lo_u32_b32 v157, -1, 0
	v_mbcnt_hi_u32_b32 v157, -1, v157
	v_lshrrev_b32_e32 v153, 1, v156
	v_lshlrev_b32_e32 v153, 13, v153
	v_and_b32_e32 v154, 1, v156
	v_lshl_add_u32 v153, v154, 9, v153
	v_lshl_add_u32 v153, v141, 1, v153
	s_add_i32 s2, s53, 0xc000
	v_add_u32_e32 v153, s2, v153
	v_lshrrev_b32_e32 v154, 3, v157
	v_and_b32_e32 v157, 7, v157
	v_lshlrev_b32_e32 v155, 4, v157
	v_lshl_add_u32 v155, v154, 7, v155
	v_add_u32_e32 v155, s2, v155
	v_add_u32_e32 v154, s33, v154
	v_mul_u32_u24_e32 v154, 0x1200, v154
	v_lshl_add_u32 v157, v157, 3, s92
	v_lshl_add_u32 v157, v157, 1, v154
	v_mov_b32_e32 v154, v155
	v_mov_b32_e32 v155, v157
	s_lshl_b32 s2, s52, 1
	s_lshl_b32 s4, s69, 3
	s_add_i32 s2, s2, s4
	s_add_i32 s2, s2, -8
	s_mul_i32 s2, s2, 0x90000
	s_lshl_b32 s4, s71, 9
	s_add_i32 s2, s2, s4
	s_add_u32 s4, s54, s2
	s_addc_u32 s5, s55, 0
	s_add_u32 s8, s4, 0x9000
	s_addc_u32 s9, s5, 0
	v_cvt_pk_bf16_f32 v122, v122, v123
	v_cvt_pk_bf16_f32 v123, v124, v125
	v_cvt_pk_bf16_f32 v106, v106, v107
	v_cvt_pk_bf16_f32 v107, v108, v109
	v_cvt_pk_bf16_f32 v90, v90, v91
	v_cvt_pk_bf16_f32 v91, v92, v93
	v_cvt_pk_bf16_f32 v74, v74, v75
	v_cvt_pk_bf16_f32 v75, v76, v77
	ds_write_b16 v153, v122 offset:0
	ds_write_b16_d16_hi v153, v122 offset:128
	ds_write_b16 v153, v123 offset:256
	ds_write_b16_d16_hi v153, v123 offset:384
	ds_write_b16 v153, v106 offset:32
	ds_write_b16_d16_hi v153, v106 offset:160
	ds_write_b16 v153, v107 offset:288
	ds_write_b16_d16_hi v153, v107 offset:416
	ds_write_b16 v153, v90 offset:64
	ds_write_b16_d16_hi v153, v90 offset:192
	ds_write_b16 v153, v91 offset:320
	ds_write_b16_d16_hi v153, v91 offset:448
	ds_write_b16 v153, v74 offset:96
	ds_write_b16_d16_hi v153, v74 offset:224
	ds_write_b16 v153, v75 offset:352
	ds_write_b16_d16_hi v153, v75 offset:480
	ds_read_b128 v[130:133], v154
	ds_read_b128 v[134:137], v154 offset:8192
	s_waitcnt lgkmcnt(0)
	global_store_dwordx4 v155, v[130:133], s[4:5]
	global_store_dwordx4 v155, v[134:137], s[8:9]
	s_nop 1
	v_cvt_pk_bf16_f32 v58, v58, v59
	v_cvt_pk_bf16_f32 v59, v60, v61
	v_cvt_pk_bf16_f32 v42, v42, v43
	v_cvt_pk_bf16_f32 v43, v44, v45
	v_cvt_pk_bf16_f32 v26, v26, v27
	v_cvt_pk_bf16_f32 v27, v28, v29
	v_cvt_pk_bf16_f32 v10, v10, v11
	v_cvt_pk_bf16_f32 v11, v12, v13
	ds_write_b16 v153, v58 offset:0
	ds_write_b16_d16_hi v153, v58 offset:128
	ds_write_b16 v153, v59 offset:256
	ds_write_b16_d16_hi v153, v59 offset:384
	ds_write_b16 v153, v42 offset:32
	ds_write_b16_d16_hi v153, v42 offset:160
	ds_write_b16 v153, v43 offset:288
	ds_write_b16_d16_hi v153, v43 offset:416
	ds_write_b16 v153, v26 offset:64
	ds_write_b16_d16_hi v153, v26 offset:192
	ds_write_b16 v153, v27 offset:320
	ds_write_b16_d16_hi v153, v27 offset:448
	ds_write_b16 v153, v10 offset:96
	ds_write_b16_d16_hi v153, v10 offset:224
	ds_write_b16 v153, v11 offset:352
	ds_write_b16_d16_hi v153, v11 offset:480
	ds_read_b128 v[130:133], v154
	ds_read_b128 v[134:137], v154 offset:8192
	s_waitcnt lgkmcnt(0)
	global_store_dwordx4 v155, v[130:133], s[4:5] offset:256
	global_store_dwordx4 v155, v[134:137], s[8:9] offset:256
	s_nop 1
	s_add_u32 s4, s4, 0x12000
	s_addc_u32 s5, s5, 0
	s_add_u32 s8, s4, 0x9000
	s_addc_u32 s9, s5, 0
	v_cvt_pk_bf16_f32 v126, v126, v127
	v_cvt_pk_bf16_f32 v127, v128, v129
	v_cvt_pk_bf16_f32 v110, v110, v111
	v_cvt_pk_bf16_f32 v111, v112, v113
	v_cvt_pk_bf16_f32 v94, v94, v95
	v_cvt_pk_bf16_f32 v95, v96, v97
	v_cvt_pk_bf16_f32 v78, v78, v79
	v_cvt_pk_bf16_f32 v79, v80, v81
	ds_write_b16 v153, v126 offset:0
	ds_write_b16_d16_hi v153, v126 offset:128
	ds_write_b16 v153, v127 offset:256
	ds_write_b16_d16_hi v153, v127 offset:384
	ds_write_b16 v153, v110 offset:32
	ds_write_b16_d16_hi v153, v110 offset:160
	ds_write_b16 v153, v111 offset:288
	ds_write_b16_d16_hi v153, v111 offset:416
	ds_write_b16 v153, v94 offset:64
	ds_write_b16_d16_hi v153, v94 offset:192
	ds_write_b16 v153, v95 offset:320
	ds_write_b16_d16_hi v153, v95 offset:448
	ds_write_b16 v153, v78 offset:96
	ds_write_b16_d16_hi v153, v78 offset:224
	ds_write_b16 v153, v79 offset:352
	ds_write_b16_d16_hi v153, v79 offset:480
	ds_read_b128 v[130:133], v154
	ds_read_b128 v[134:137], v154 offset:8192
	s_waitcnt lgkmcnt(0)
	global_store_dwordx4 v155, v[130:133], s[4:5]
	global_store_dwordx4 v155, v[134:137], s[8:9]
	s_nop 1
	v_cvt_pk_bf16_f32 v62, v62, v63
	v_cvt_pk_bf16_f32 v63, v64, v65
	v_cvt_pk_bf16_f32 v46, v46, v47
	v_cvt_pk_bf16_f32 v47, v48, v49
	v_cvt_pk_bf16_f32 v30, v30, v31
	v_cvt_pk_bf16_f32 v31, v32, v33
	v_cvt_pk_bf16_f32 v14, v14, v15
	v_cvt_pk_bf16_f32 v15, v16, v17
	ds_write_b16 v153, v62 offset:0
	ds_write_b16_d16_hi v153, v62 offset:128
	ds_write_b16 v153, v63 offset:256
	ds_write_b16_d16_hi v153, v63 offset:384
	ds_write_b16 v153, v46 offset:32
	ds_write_b16_d16_hi v153, v46 offset:160
	ds_write_b16 v153, v47 offset:288
	ds_write_b16_d16_hi v153, v47 offset:416
	ds_write_b16 v153, v30 offset:64
	ds_write_b16_d16_hi v153, v30 offset:192
	ds_write_b16 v153, v31 offset:320
	ds_write_b16_d16_hi v153, v31 offset:448
	ds_write_b16 v153, v14 offset:96
	ds_write_b16_d16_hi v153, v14 offset:224
	ds_write_b16 v153, v15 offset:352
	ds_write_b16_d16_hi v153, v15 offset:480
	ds_read_b128 v[130:133], v154
	ds_read_b128 v[134:137], v154 offset:8192
	s_waitcnt lgkmcnt(0)
; __device__ __forceinline__ unsigned pk2(float lo, float hi) { const f32x2_t v = {lo, hi}; const bf16v2_t b = __builtin_convertvector(v, bf16v2_t); return __builtin_bit_cast(unsigned, b); }
;     __device__ __forceinline__ void operator()(const AccT& acc, const pg8::Unit& u, int wr, int wc, int fr_, int fq_) const {
;     ...
;         } else if (pn < 8) {
; #pragma unroll
;             for (int ai = 0; ai < 2; ++ai)
; #pragma unroll
;                 for (int m = 0; m < 4; ++m) {
;                     const int rl = rl0 + ai * 128 + m * 16;
; #pragma unroll
;                     for (int bj = 0; bj < 2; ++bj) {
;                         const int hv = 2 * (pn - 4) + bj;
; #pragma unroll
;                         for (int n = 0; n < 2; ++n) {
;                             const int dv = 32 * wc + 16 * n + 4 * fq;
;                             bf16_t* vt = VT + ((size_t)(b * NH + hv) * DV + dv) * TB + pt * 256 + rl;
;                             const f32x4 a = acc[ai][bj][m][n];
;                             const unsigned p0 = pk2(a[0], a[1]), p1 = pk2(a[2], a[3]);
;                             vt[0] = (bf16_t)(p0 & 0xffffu); vt[(size_t)TB] = (bf16_t)(p0 >> 16); vt[(size_t)2 * TB] = (bf16_t)(p1 & 0xffffu); vt[(size_t)3 * TB] = (bf16_t)(p1 >> 16);
;                         }
;                         __builtin_amdgcn_sched_barrier(0);
;                     }
;                 }
	global_store_dwordx4 v155, v[130:133], s[4:5] offset:256
	global_store_dwordx4 v155, v[134:137], s[8:9] offset:256
	s_nop 1
	s_add_u32 s4, s4, 0x7e000
	s_addc_u32 s5, s5, 0
	s_add_u32 s8, s4, 0x9000
	s_addc_u32 s9, s5, 0
	v_cvt_pk_bf16_f32 v114, v114, v115
	v_cvt_pk_bf16_f32 v115, v116, v117
	v_cvt_pk_bf16_f32 v98, v98, v99
	v_cvt_pk_bf16_f32 v99, v100, v101
	v_cvt_pk_bf16_f32 v82, v82, v83
	v_cvt_pk_bf16_f32 v83, v84, v85
	v_cvt_pk_bf16_f32 v66, v66, v67
	v_cvt_pk_bf16_f32 v67, v68, v69
	ds_write_b16 v153, v114 offset:0
	ds_write_b16_d16_hi v153, v114 offset:128
	ds_write_b16 v153, v115 offset:256
	ds_write_b16_d16_hi v153, v115 offset:384
	ds_write_b16 v153, v98 offset:32
	ds_write_b16_d16_hi v153, v98 offset:160
	ds_write_b16 v153, v99 offset:288
	ds_write_b16_d16_hi v153, v99 offset:416
	ds_write_b16 v153, v82 offset:64
	ds_write_b16_d16_hi v153, v82 offset:192
	ds_write_b16 v153, v83 offset:320
	ds_write_b16_d16_hi v153, v83 offset:448
	ds_write_b16 v153, v66 offset:96
	ds_write_b16_d16_hi v153, v66 offset:224
	ds_write_b16 v153, v67 offset:352
	ds_write_b16_d16_hi v153, v67 offset:480
	ds_read_b128 v[130:133], v154
	ds_read_b128 v[134:137], v154 offset:8192
	s_waitcnt lgkmcnt(0)
	global_store_dwordx4 v155, v[130:133], s[4:5]
	global_store_dwordx4 v155, v[134:137], s[8:9]
	s_nop 1
	v_cvt_pk_bf16_f32 v50, v50, v51
	v_cvt_pk_bf16_f32 v51, v52, v53
	v_cvt_pk_bf16_f32 v34, v34, v35
	v_cvt_pk_bf16_f32 v35, v36, v37
	v_cvt_pk_bf16_f32 v18, v18, v19
	v_cvt_pk_bf16_f32 v19, v20, v21
	v_cvt_pk_bf16_f32 v6, v6, v7
	v_cvt_pk_bf16_f32 v7, v8, v9
	ds_write_b16 v153, v50 offset:0
	ds_write_b16_d16_hi v153, v50 offset:128
	ds_write_b16 v153, v51 offset:256
	ds_write_b16_d16_hi v153, v51 offset:384
	ds_write_b16 v153, v34 offset:32
	ds_write_b16_d16_hi v153, v34 offset:160
	ds_write_b16 v153, v35 offset:288
	ds_write_b16_d16_hi v153, v35 offset:416
	ds_write_b16 v153, v18 offset:64
	ds_write_b16_d16_hi v153, v18 offset:192
	ds_write_b16 v153, v19 offset:320
	ds_write_b16_d16_hi v153, v19 offset:448
	ds_write_b16 v153, v6 offset:96
	ds_write_b16_d16_hi v153, v6 offset:224
	ds_write_b16 v153, v7 offset:352
	ds_write_b16_d16_hi v153, v7 offset:480
	ds_read_b128 v[130:133], v154
	ds_read_b128 v[134:137], v154 offset:8192
	s_waitcnt lgkmcnt(0)
	global_store_dwordx4 v155, v[130:133], s[4:5] offset:256
	global_store_dwordx4 v155, v[134:137], s[8:9] offset:256
	s_nop 1
	s_add_u32 s4, s4, 0x12000
	s_addc_u32 s5, s5, 0
	s_add_u32 s8, s4, 0x9000
	s_addc_u32 s9, s5, 0
	v_cvt_pk_bf16_f32 v118, v118, v119
	v_cvt_pk_bf16_f32 v119, v120, v121
	v_cvt_pk_bf16_f32 v102, v102, v103
	v_cvt_pk_bf16_f32 v103, v104, v105
	v_cvt_pk_bf16_f32 v86, v86, v87
	v_cvt_pk_bf16_f32 v87, v88, v89
	v_cvt_pk_bf16_f32 v70, v70, v71
	v_cvt_pk_bf16_f32 v71, v72, v73
	ds_write_b16 v153, v118 offset:0
	ds_write_b16_d16_hi v153, v118 offset:128
	ds_write_b16 v153, v119 offset:256
	ds_write_b16_d16_hi v153, v119 offset:384
	ds_write_b16 v153, v102 offset:32
	ds_write_b16_d16_hi v153, v102 offset:160
	ds_write_b16 v153, v103 offset:288
	ds_write_b16_d16_hi v153, v103 offset:416
	ds_write_b16 v153, v86 offset:64
	ds_write_b16_d16_hi v153, v86 offset:192
	ds_write_b16 v153, v87 offset:320
	ds_write_b16_d16_hi v153, v87 offset:448
	ds_write_b16 v153, v70 offset:96
	ds_write_b16_d16_hi v153, v70 offset:224
	ds_write_b16 v153, v71 offset:352
	ds_write_b16_d16_hi v153, v71 offset:480
	ds_read_b128 v[130:133], v154
	ds_read_b128 v[134:137], v154 offset:8192
	s_waitcnt lgkmcnt(0)
	global_store_dwordx4 v155, v[130:133], s[4:5]
	global_store_dwordx4 v155, v[134:137], s[8:9]
	s_nop 1
	v_cvt_pk_bf16_f32 v54, v54, v55
	v_cvt_pk_bf16_f32 v55, v56, v57
	v_cvt_pk_bf16_f32 v38, v38, v39
	v_cvt_pk_bf16_f32 v39, v40, v41
	v_cvt_pk_bf16_f32 v22, v22, v23
	v_cvt_pk_bf16_f32 v23, v24, v25
	v_cvt_pk_bf16_f32 v2, v2, v3
	v_cvt_pk_bf16_f32 v3, v4, v5
	ds_write_b16 v153, v54 offset:0
	ds_write_b16_d16_hi v153, v54 offset:128
	ds_write_b16 v153, v55 offset:256
	ds_write_b16_d16_hi v153, v55 offset:384
	ds_write_b16 v153, v38 offset:32
	ds_write_b16_d16_hi v153, v38 offset:160
	ds_write_b16 v153, v39 offset:288
	ds_write_b16_d16_hi v153, v39 offset:416
	ds_write_b16 v153, v22 offset:64
	ds_write_b16_d16_hi v153, v22 offset:192
	ds_write_b16 v153, v23 offset:320
	ds_write_b16_d16_hi v153, v23 offset:448
	ds_write_b16 v153, v2 offset:96
	ds_write_b16_d16_hi v153, v2 offset:224
	ds_write_b16 v153, v3 offset:352
	ds_write_b16_d16_hi v153, v3 offset:480
	ds_read_b128 v[130:133], v154
	ds_read_b128 v[134:137], v154 offset:8192
	s_waitcnt lgkmcnt(0)
	global_store_dwordx4 v155, v[130:133], s[4:5] offset:256
	global_store_dwordx4 v155, v[134:137], s[8:9] offset:256
	s_nop 1
.LBB0_263:
	s_mov_b32 s32, 1
	s_cbranch_execz .LBB0_266

; template <class Epi>
; __device__ __forceinline__ void gemm_phase(LAS unsigned char* lds, const Gemm g, const Epi& E) {
;     ...
;         if (!(Epi::KEEP && cur.sub == 0))
; #pragma unroll
;         for (int a = 0; a < 2; ++a)
; #pragma unroll
;             for (int b = 0; b < 2; ++b)
; #pragma unroll
;                 for (int m = 0; m < 4; ++m)
; #pragma unroll
;                     for (int n = 0; n < 2; ++n) acc[a][b][m][n] = (f32x4){0.f, 0.f, 0.f, 0.f};
;         ++ui; get_unit(lds, ui, cur); cA = nA; cB = nB;
.LBB0_268:
	v_mov_b64_e32 v[2:3], 0
	v_mov_b64_e32 v[4:5], 0
	v_mov_b64_e32 v[6:7], 0
	v_mov_b64_e32 v[8:9], 0
	v_mov_b64_e32 v[10:11], 0
	v_mov_b64_e32 v[12:13], 0
	v_mov_b64_e32 v[14:15], 0
	v_mov_b64_e32 v[16:17], 0
	v_mov_b64_e32 v[18:19], 0
	v_mov_b64_e32 v[20:21], 0
	v_mov_b64_e32 v[22:23], 0
	v_mov_b64_e32 v[24:25], 0
	v_mov_b64_e32 v[26:27], 0
	v_mov_b64_e32 v[28:29], 0
	v_mov_b64_e32 v[30:31], 0
	v_mov_b64_e32 v[32:33], 0
	v_mov_b64_e32 v[34:35], 0
	v_mov_b64_e32 v[36:37], 0
	v_mov_b64_e32 v[38:39], 0
	v_mov_b64_e32 v[40:41], 0
	v_mov_b64_e32 v[42:43], 0
	v_mov_b64_e32 v[44:45], 0
	v_mov_b64_e32 v[46:47], 0
	v_mov_b64_e32 v[48:49], 0
	v_mov_b64_e32 v[50:51], 0
	v_mov_b64_e32 v[52:53], 0
	v_mov_b64_e32 v[54:55], 0
	v_mov_b64_e32 v[56:57], 0
	v_mov_b64_e32 v[58:59], 0
	v_mov_b64_e32 v[60:61], 0
	v_mov_b64_e32 v[62:63], 0
	v_mov_b64_e32 v[64:65], 0
	v_mov_b64_e32 v[66:67], 0
	v_mov_b64_e32 v[68:69], 0
	v_mov_b64_e32 v[70:71], 0
	v_mov_b64_e32 v[72:73], 0
	v_mov_b64_e32 v[74:75], 0
	v_mov_b64_e32 v[76:77], 0
	v_mov_b64_e32 v[78:79], 0
	v_mov_b64_e32 v[80:81], 0
	v_mov_b64_e32 v[82:83], 0
	v_mov_b64_e32 v[84:85], 0
	v_mov_b64_e32 v[86:87], 0
	v_mov_b64_e32 v[88:89], 0
	v_mov_b64_e32 v[90:91], 0
	v_mov_b64_e32 v[92:93], 0
	v_mov_b64_e32 v[94:95], 0
	v_mov_b64_e32 v[96:97], 0
	v_mov_b64_e32 v[98:99], 0
	v_mov_b64_e32 v[100:101], 0
	v_mov_b64_e32 v[102:103], 0
	v_mov_b64_e32 v[104:105], 0
	v_mov_b64_e32 v[106:107], 0
	v_mov_b64_e32 v[108:109], 0
	v_mov_b64_e32 v[110:111], 0
	v_mov_b64_e32 v[112:113], 0
	v_mov_b64_e32 v[114:115], 0
	v_mov_b64_e32 v[116:117], 0
	v_mov_b64_e32 v[118:119], 0
	v_mov_b64_e32 v[120:121], 0
	v_mov_b64_e32 v[122:123], 0
	v_mov_b64_e32 v[124:125], 0
	v_mov_b64_e32 v[126:127], 0
	v_mov_b64_e32 v[128:129], 0
	s_and_b64 vcc, exec, s[66:67]
	s_cbranch_vccnz .LBB0_97
	s_branch .LBB0_98

; #define LAS __attribute__((address_space(3)))
; __device__ __forceinline__ void build_units(LAS unsigned char* lds, const Sched& S) {
;     const int t = threadIdx.x;
;     if (t < 16) {
;         int valid, pm, pn, sub, kt0, nt, sp;
;         S.entry(t, valid, pm, pn, sub, kt0, nt, sp);
;         asm volatile("" : "+v"(kt0), "+v"(nt), "+v"(sp), "+v"(valid));
;         LAS int* e = (LAS int*)(lds + 131072 + 64) + 8 * t;
;         e[0] = valid; e[1] = pm; e[2] = pn; e[3] = sub; e[4] = kt0; e[5] = nt; e[6] = sp; e[7] = 0;
;     }
;     __syncthreads();
; }
.LBB0_394:
	v_readlane_b32 s14, v254, 26
	v_readlane_b32 s15, v254, 27
	s_lshr_b32 s2, s10, 6
	s_or_b64 s[6:7], s[6:7], s[14:15]
	s_and_b64 s[6:7], s[6:7], exec
	s_cselect_b32 s11, 0x3e8, 1
	s_lshr_b32 s6, s10, 7
	s_lshr_b32 s14, s10, 10
	s_and_b32 s6, s6, 6
	s_mul_i32 s7, s74, s14
	s_min_u32 s15, s74, s6
	s_add_i32 s15, s15, s7
	s_lshl_b32 s15, s15, 1
	s_cmp_lt_u32 s74, s6
	v_cmp_eq_u32_e32 vcc, s11, v138
	s_cselect_b64 s[6:7], -1, 0
	v_cndmask_b32_e64 v4, 0, 1, s[8:9]
	v_cndmask_b32_e64 v3, 0, 1, vcc
	v_cmp_gt_u32_e32 vcc, s11, v138
	s_cmp_lg_u64 s[6:7], 0
	s_addc_u32 s6, s14, 0
	v_cndmask_b32_e32 v3, v3, v4, vcc
	v_and_b32_e32 v4, 1, v3
	v_mov_b32_e32 v3, s15
	s_lshl_b32 s6, s6, 1
	v_cndmask_b32_e64 v8, v3, 0, vcc
	v_mov_b32_e32 v3, s74
	v_cndmask_b32_e64 v10, v3, 0, vcc
	v_mov_b32_e32 v3, s6
	v_mov_b32_e32 v5, s2
	v_cndmask_b32_e32 v9, v3, v5, vcc
	v_mov_b32_e32 v3, s33
	v_cndmask_b32_e32 v6, v3, v0, vcc
	v_mov_b32_e32 v0, s68
	v_cndmask_b32_e32 v5, v0, v2, vcc
	v_add_u32_e32 v0, 0, v139
	v_cndmask_b32_e64 v7, 2, 0, vcc
	v_add_u32_e32 v0, 0x20040, v0
	v_mov_b32_e32 v11, v1
	v_readlane_b32 s98, v4, 1
	v_readlane_b32 s99, v254, 21
	s_nop 1
	s_and_b32 s99, s99, 1
	s_cmp_lg_u32 s98, 0
	s_cselect_b32 s99, s99, 0
	s_lshl_b32 s99, s99, 5
	v_mov_b32_e32 v2, s99
	v_cmp_gt_u32_e32 vcc, 2, v138
	s_nop 1
	v_cndmask_b32_e32 v2, 0, v2, vcc
	v_xor_b32_e32 v0, v0, v2
	ds_write_b128 v0, v[4:7]
	ds_write_b128 v0, v[8:11] offset:16

; template <class Epi>
; __device__ __forceinline__ void gemm_phase(LAS unsigned char* lds, const Gemm g, const Epi& E) {
;     ...
;         if (!(Epi::KEEP && cur.sub == 0))
; #pragma unroll
;         for (int a = 0; a < 2; ++a)
; #pragma unroll
;             for (int b = 0; b < 2; ++b)
; #pragma unroll
;                 for (int m = 0; m < 4; ++m)
; #pragma unroll
;                     for (int n = 0; n < 2; ++n) acc[a][b][m][n] = (f32x4){0.f, 0.f, 0.f, 0.f};
;         ++ui; get_unit(lds, ui, cur); cA = nA; cB = nB;
.LBB0_406:
	s_add_i32 s7, s70, -2
	s_add_u32 s62, s62, 0x80
	s_addc_u32 s63, s63, 0
	s_add_u32 s15, s4, 0x100
	s_addc_u32 s53, s5, 0
	s_mov_b32 s4, 0
	v_mov_b64_e32 v[2:3], 0
	v_mov_b64_e32 v[4:5], 0
	v_mov_b64_e32 v[6:7], 0
	v_mov_b64_e32 v[8:9], 0
	v_mov_b64_e32 v[10:11], 0
	v_mov_b64_e32 v[12:13], 0
	v_mov_b64_e32 v[14:15], 0
	v_mov_b64_e32 v[16:17], 0
	v_mov_b64_e32 v[18:19], 0
	v_mov_b64_e32 v[20:21], 0
	v_mov_b64_e32 v[22:23], 0
	v_mov_b64_e32 v[24:25], 0
	v_mov_b64_e32 v[26:27], 0
	v_mov_b64_e32 v[28:29], 0
	v_mov_b64_e32 v[30:31], 0
	v_mov_b64_e32 v[32:33], 0
	v_mov_b64_e32 v[34:35], 0
	v_mov_b64_e32 v[36:37], 0
	v_mov_b64_e32 v[38:39], 0
	v_mov_b64_e32 v[40:41], 0
	v_mov_b64_e32 v[42:43], 0
	v_mov_b64_e32 v[44:45], 0
	v_mov_b64_e32 v[46:47], 0
	v_mov_b64_e32 v[48:49], 0
	v_mov_b64_e32 v[50:51], 0
	v_mov_b64_e32 v[52:53], 0
	v_mov_b64_e32 v[54:55], 0
	v_mov_b64_e32 v[56:57], 0
	v_mov_b64_e32 v[58:59], 0
	v_mov_b64_e32 v[60:61], 0
	v_mov_b64_e32 v[62:63], 0
	v_mov_b64_e32 v[64:65], 0
	v_mov_b64_e32 v[66:67], 0
	v_mov_b64_e32 v[68:69], 0
	v_mov_b64_e32 v[70:71], 0
	v_mov_b64_e32 v[72:73], 0
	v_mov_b64_e32 v[74:75], 0
	v_mov_b64_e32 v[76:77], 0
	v_mov_b64_e32 v[78:79], 0
	v_mov_b64_e32 v[80:81], 0
	v_mov_b64_e32 v[82:83], 0
	v_mov_b64_e32 v[84:85], 0
	v_mov_b64_e32 v[86:87], 0
	v_mov_b64_e32 v[88:89], 0
	v_mov_b64_e32 v[90:91], 0
	v_mov_b64_e32 v[92:93], 0
	v_mov_b64_e32 v[94:95], 0
	v_mov_b64_e32 v[96:97], 0
	v_mov_b64_e32 v[98:99], 0
	v_mov_b64_e32 v[100:101], 0
	v_mov_b64_e32 v[102:103], 0
	v_mov_b64_e32 v[104:105], 0
	v_mov_b64_e32 v[106:107], 0
	v_mov_b64_e32 v[108:109], 0
	v_mov_b64_e32 v[110:111], 0
	v_mov_b64_e32 v[112:113], 0
	v_mov_b64_e32 v[114:115], 0
	v_mov_b64_e32 v[116:117], 0
	v_mov_b64_e32 v[118:119], 0
	v_mov_b64_e32 v[120:121], 0
	v_mov_b64_e32 v[122:123], 0
	v_mov_b64_e32 v[124:125], 0
	v_mov_b64_e32 v[126:127], 0
	v_mov_b64_e32 v[128:129], 0

; template <class Epi>
; __device__ __forceinline__ void gemm_phase(LAS unsigned char* lds, const Gemm g, const Epi& E) {
;     ...
;         if (!(Epi::KEEP && cur.sub == 0))
; #pragma unroll
;         for (int a = 0; a < 2; ++a)
; #pragma unroll
;             for (int b = 0; b < 2; ++b)
; #pragma unroll
;                 for (int m = 0; m < 4; ++m)
; #pragma unroll
;                     for (int n = 0; n < 2; ++n) acc[a][b][m][n] = (f32x4){0.f, 0.f, 0.f, 0.f};
;         ++ui; get_unit(lds, ui, cur); cA = nA; cB = nB;
.LBB0_415:
	v_mov_b64_e32 v[2:3], 0
	v_mov_b64_e32 v[4:5], 0
	v_mov_b64_e32 v[6:7], 0
	v_mov_b64_e32 v[8:9], 0
	v_mov_b64_e32 v[10:11], 0
	v_mov_b64_e32 v[12:13], 0
	v_mov_b64_e32 v[14:15], 0
	v_mov_b64_e32 v[16:17], 0
	v_mov_b64_e32 v[18:19], 0
	v_mov_b64_e32 v[20:21], 0
	v_mov_b64_e32 v[22:23], 0
	v_mov_b64_e32 v[24:25], 0
	v_mov_b64_e32 v[26:27], 0
	v_mov_b64_e32 v[28:29], 0
	v_mov_b64_e32 v[30:31], 0
	v_mov_b64_e32 v[32:33], 0
	v_mov_b64_e32 v[34:35], 0
	v_mov_b64_e32 v[36:37], 0
	v_mov_b64_e32 v[38:39], 0
	v_mov_b64_e32 v[40:41], 0
	v_mov_b64_e32 v[42:43], 0
	v_mov_b64_e32 v[44:45], 0
	v_mov_b64_e32 v[46:47], 0
	v_mov_b64_e32 v[48:49], 0
	v_mov_b64_e32 v[50:51], 0
	v_mov_b64_e32 v[52:53], 0
	v_mov_b64_e32 v[54:55], 0
	v_mov_b64_e32 v[56:57], 0
	v_mov_b64_e32 v[58:59], 0
	v_mov_b64_e32 v[60:61], 0
	v_mov_b64_e32 v[62:63], 0
	v_mov_b64_e32 v[64:65], 0
	v_mov_b64_e32 v[66:67], 0
	v_mov_b64_e32 v[68:69], 0
	v_mov_b64_e32 v[70:71], 0
	v_mov_b64_e32 v[72:73], 0
	v_mov_b64_e32 v[74:75], 0
	v_mov_b64_e32 v[76:77], 0
	v_mov_b64_e32 v[78:79], 0
	v_mov_b64_e32 v[80:81], 0
	v_mov_b64_e32 v[82:83], 0
	v_mov_b64_e32 v[84:85], 0
	v_mov_b64_e32 v[86:87], 0
	v_mov_b64_e32 v[88:89], 0
	v_mov_b64_e32 v[90:91], 0
	v_mov_b64_e32 v[92:93], 0
	v_mov_b64_e32 v[94:95], 0
	v_mov_b64_e32 v[96:97], 0
	v_mov_b64_e32 v[98:99], 0
	v_mov_b64_e32 v[100:101], 0
	v_mov_b64_e32 v[102:103], 0
	v_mov_b64_e32 v[104:105], 0
	v_mov_b64_e32 v[106:107], 0
	v_mov_b64_e32 v[108:109], 0
	v_mov_b64_e32 v[110:111], 0
	v_mov_b64_e32 v[112:113], 0
	v_mov_b64_e32 v[114:115], 0
	v_mov_b64_e32 v[116:117], 0
	v_mov_b64_e32 v[118:119], 0
	v_mov_b64_e32 v[120:121], 0
	v_mov_b64_e32 v[122:123], 0
	v_mov_b64_e32 v[124:125], 0
	v_mov_b64_e32 v[126:127], 0
	v_mov_b64_e32 v[128:129], 0
	s_and_b64 vcc, exec, s[12:13]
	s_cbranch_vccnz .LBB0_409
	s_branch .LBB0_410

; #define PG8_STAGE(bufoff, gbase, voff) do { _Pragma("unroll") for (int _i = 0; _i < 2; ++_i) \
;         __builtin_amdgcn_global_load_lds((const unsigned*)((const char*)(gbase) + (voff)[_i]), (LAS unsigned*)(lds + (bufoff) + ldsw + _i * 8192), 16, 0, 0); } while (0)
; #define PG8_WAIT_V(n) asm volatile("s_waitcnt vmcnt(" #n ")" ::: "memory")
; #define PG8_BAR __builtin_amdgcn_s_barrier()
; template <class Epi>
; __device__ __forceinline__ void gemm_phase(LAS unsigned char* lds, const Gemm g, const Epi& E) {
;     ...
;     f32x4 acc[2][2][4][2];
; #pragma unroll
;     for (int a = 0; a < 2; ++a)
; #pragma unroll
;         for (int b = 0; b < 2; ++b)
; #pragma unroll
;             for (int m = 0; m < 4; ++m)
; #pragma unroll
;                 for (int n = 0; n < 2; ++n) acc[a][b][m][n] = (f32x4){0.f, 0.f, 0.f, 0.f};
;     bf16x8 At[4][2], B0[2][2], B1[2][2];
;     const char* cA = (const char*)((cur.sub & 1) ? g.A1 : g.A0) + (size_t)cur.pm * tstep + (size_t)cur.kt0 * kstep; const char* cB = (const char*)((cur.sub & 1) ? g.B1 : g.B0) + (size_t)cur.pn * tstep + (size_t)cur.kt0 * kstep;
;     PG8_STAGE(PG8_SB(0, 0), cB, voffA); PG8_STAGE(PG8_SB(0, 1), cB + hstep, voffA); PG8_STAGE(PG8_SA(0, 0), cA, voffA); PG8_STAGE(PG8_SA(0, 1), cA + hstep, voffA);
;     if (wr == 1) PG8_BAR;
;     PG8_WAIT_V(2); PG8_BAR;
;     PG8_STAGE(PG8_SB(1, 0), cB + kstep, voffA); PG8_STAGE(PG8_SA(1, 0), cA + kstep, voffA); PG8_STAGE(PG8_SB(1, 1), cB + hstep + kstep, voffA);
;     PG8_WAIT_V(6); PG8_BAR;
;     for (;;) {
;         Unit nxt; const bool has_next = get_unit(lds, ui + 1, nxt);
;         const char* nA = has_next ? (const char*)((nxt.sub & 1) ? g.A1 : g.A0) + (size_t)nxt.pm * tstep + (size_t)nxt.kt0 * kstep : cA; const char* nB = has_next ? (const char*)((nxt.sub & 1) ? g.B1 : g.B0) + (size_t)nxt.pn * tstep + (size_t)nxt.kt0 * kstep : cB;
.LBB0_439:
	s_ashr_i32 s15, s14, 31
	s_lshl_b64 s[58:59], s[14:15], 19
	s_add_u32 s15, s35, s58
	s_addc_u32 s55, s28, s59
	s_ashr_i32 s57, s56, 31
	s_lshl_b64 s[62:63], s[56:57], 7
	s_add_u32 s58, s15, s62
	s_addc_u32 s59, s55, s63
	s_ashr_i32 s55, s54, 31
	s_lshl_b64 s[70:71], s[54:55], 19
	s_add_u32 s15, s20, s70
	s_addc_u32 s55, s26, s71
	s_add_u32 s62, s15, s62
	s_addc_u32 s63, s55, s63
	s_cmp_lt_i32 s37, 1
	s_cbranch_scc1 .LBB0_449
	s_and_b64 s[70:71], s[66:67], exec
	s_cselect_b32 s15, s59, s69
	s_cselect_b32 s55, s58, s68
	s_cselect_b32 s57, s63, s5
	s_cselect_b32 s82, s62, s4
	s_add_i32 s92, s37, -2
	s_add_u32 s68, s68, 0x40080
	s_addc_u32 s69, s69, 0
	s_add_u32 s93, s4, 0x100
	s_addc_u32 vcc_lo, s5, 0
	s_mov_b32 s4, 0
	v_mov_b64_e32 v[2:3], 0
	v_mov_b64_e32 v[4:5], 0
	v_mov_b64_e32 v[6:7], 0
	v_mov_b64_e32 v[8:9], 0
	v_mov_b64_e32 v[10:11], 0
	v_mov_b64_e32 v[12:13], 0
	v_mov_b64_e32 v[14:15], 0
	v_mov_b64_e32 v[16:17], 0
	v_mov_b64_e32 v[18:19], 0
	v_mov_b64_e32 v[20:21], 0
	v_mov_b64_e32 v[22:23], 0
	v_mov_b64_e32 v[24:25], 0
	v_mov_b64_e32 v[26:27], 0
	v_mov_b64_e32 v[28:29], 0
	v_mov_b64_e32 v[30:31], 0
	v_mov_b64_e32 v[32:33], 0
	v_mov_b64_e32 v[34:35], 0
	v_mov_b64_e32 v[36:37], 0
	v_mov_b64_e32 v[38:39], 0
	v_mov_b64_e32 v[40:41], 0
	v_mov_b64_e32 v[42:43], 0
	v_mov_b64_e32 v[44:45], 0
	v_mov_b64_e32 v[46:47], 0
	v_mov_b64_e32 v[48:49], 0
	v_mov_b64_e32 v[50:51], 0
	v_mov_b64_e32 v[52:53], 0
	v_mov_b64_e32 v[54:55], 0
	v_mov_b64_e32 v[56:57], 0
	v_mov_b64_e32 v[58:59], 0
	v_mov_b64_e32 v[60:61], 0
	v_mov_b64_e32 v[62:63], 0
	v_mov_b64_e32 v[64:65], 0
	v_mov_b64_e32 v[66:67], 0
	v_mov_b64_e32 v[68:69], 0
	v_mov_b64_e32 v[70:71], 0
	v_mov_b64_e32 v[72:73], 0
	v_mov_b64_e32 v[74:75], 0
	v_mov_b64_e32 v[76:77], 0
	v_mov_b64_e32 v[78:79], 0
	v_mov_b64_e32 v[80:81], 0
	v_mov_b64_e32 v[82:83], 0
	v_mov_b64_e32 v[84:85], 0
	v_mov_b64_e32 v[86:87], 0
	v_mov_b64_e32 v[88:89], 0
	v_mov_b64_e32 v[90:91], 0
	v_mov_b64_e32 v[92:93], 0
	v_mov_b64_e32 v[94:95], 0
	v_mov_b64_e32 v[96:97], 0
	v_mov_b64_e32 v[98:99], 0
	v_mov_b64_e32 v[100:101], 0
	v_mov_b64_e32 v[102:103], 0
	v_mov_b64_e32 v[104:105], 0
	v_mov_b64_e32 v[106:107], 0
	v_mov_b64_e32 v[108:109], 0
	v_mov_b64_e32 v[110:111], 0
	v_mov_b64_e32 v[112:113], 0
	v_mov_b64_e32 v[114:115], 0
	v_mov_b64_e32 v[116:117], 0
	v_mov_b64_e32 v[118:119], 0
	v_mov_b64_e32 v[120:121], 0
	v_mov_b64_e32 v[122:123], 0
	v_mov_b64_e32 v[124:125], 0
	v_mov_b64_e32 v[126:127], 0
	v_mov_b64_e32 v[128:129], 0
	s_cmp_lg_u32 s32, 0
	s_cbranch_scc1 .Lk3_peel
